# B1 prep: P stores of column blocks 0-2 parked in AGPRs and issued at item end so later loads do not queue behind draining stores
# baseline (speedup 1.0000x reference)
.LBB0_456:
	s_or_b64 exec, exec, s[20:21]
	s_waitcnt lgkmcnt(7)
	v_add_f32_e32 v0, v66, v0
	v_readlane_b32 s0, v214, 6
	v_mul_f32_e64 v66, |v0|, s87
	v_readlane_b32 s1, v214, 7
	v_exp_f32_e32 v66, v66
	s_movk_i32 s2, 0x600
	v_mov_b64_e32 v[80:81], s[0:1]
	v_mad_u64_u32 v[80:81], s[0:1], v78, s2, v[80:81]
	v_mov_b32_e32 v78, v81
	v_mad_u64_u32 v[78:79], s[0:1], v79, s2, v[78:79]
	v_add_f32_e32 v66, 1.0, v66
	s_mov_b32 s2, 0x800000
	v_cmp_gt_f32_e32 vcc, s2, v66
	s_mov_b32 s20, 0x3f317217
	s_mov_b32 s21, 0x7f800000
	v_cndmask_b32_e64 v82, 0, 32, vcc
	v_ldexp_f32 v66, v66, v82
	v_log_f32_e32 v66, v66
	v_max_f32_e64 v0, -v0, 0
	v_add_f32_e32 v1, v67, v1
	s_waitcnt lgkmcnt(6)
	v_add_f32_e32 v48, v52, v48
	v_mul_f32_e32 v83, 0x3f317217, v66
	v_fma_f32 v83, v66, s20, -v83
	v_fmac_f32_e32 v83, 0x3377d1cf, v66
	v_fmac_f32_e32 v83, 0x3f317217, v66
	v_cmp_lt_f32_e64 s[0:1], |v66|, s21
	v_mul_f32_e32 v48, 0xbfb8aa3b, v48
	v_add_f32_e32 v49, v53, v49
	v_cndmask_b32_e64 v66, v66, v83, s[0:1]
	v_cndmask_b32_e32 v83, 0, v197, vcc
	v_sub_f32_e32 v66, v66, v83
	v_add_f32_e32 v0, v0, v66
	v_mul_f32_e64 v66, |v1|, s87
	v_exp_f32_e32 v66, v66
	v_exp_f32_e32 v48, v48
	v_mul_f32_e32 v49, 0xbfb8aa3b, v49
	v_exp_f32_e32 v49, v49
	v_add_f32_e32 v52, 1.0, v66
	v_cmp_gt_f32_e32 vcc, s2, v52
	v_add_f32_e32 v48, 1.0, v48
	v_rcp_f32_e32 v152, v48
	v_cndmask_b32_e64 v66, 0, 32, vcc
	v_ldexp_f32 v52, v52, v66
	v_log_f32_e32 v52, v52
	v_add_f32_e32 v48, 1.0, v49
	v_add_f32_e32 v2, v68, v2
	v_max_f32_e64 v1, -v1, 0
	v_mul_f32_e32 v66, 0x3f317217, v52
	v_fma_f32 v66, v52, s20, -v66
	v_fmac_f32_e32 v66, 0x3377d1cf, v52
	v_fmac_f32_e32 v66, 0x3f317217, v52
	v_cmp_lt_f32_e64 s[0:1], |v52|, s21
	v_rcp_f32_e32 v153, v48
	v_mul_f32_e64 v48, |v2|, s87
	v_cndmask_b32_e64 v52, v52, v66, s[0:1]
	v_cndmask_b32_e32 v66, 0, v197, vcc
	v_sub_f32_e32 v52, v52, v66
	v_add_f32_e32 v1, v1, v52
	v_exp_f32_e32 v52, v48
	v_mov_b32_e32 v81, v78
	v_lshlrev_b32_e32 v78, 16, v72
	v_and_b32_e32 v79, 0xffff0000, v72
	s_waitcnt vmcnt(1)
	v_pk_add_f32 v[48:49], v[56:57], v[78:79] neg_lo:[0,1] neg_hi:[0,1]
	v_max_f32_e64 v2, -v2, 0
	s_waitcnt lgkmcnt(1)
	v_pk_fma_f32 v[168:169], v[44:45], v[48:49], v[78:79]
	v_add_f32_e32 v48, 1.0, v52
	v_cmp_gt_f32_e32 vcc, s2, v48
	v_pk_add_f32 v[44:45], v[152:153], -1.0 op_sel_hi:[1,0]
	v_add_f32_e32 v3, v69, v3
	v_cndmask_b32_e64 v49, 0, 32, vcc
	v_ldexp_f32 v48, v48, v49
	v_log_f32_e32 v48, v48
	v_pk_fma_f32 v[40:41], v[40:41], v[44:45], 1.0 op_sel_hi:[1,1,0]
	v_cndmask_b32_e32 v45, 0, v197, vcc
	v_sub_f32_e32 v0, -0.5, v0
	v_mul_f32_e32 v44, 0x3f317217, v48
	v_fma_f32 v44, v48, s20, -v44
	v_fmac_f32_e32 v44, 0x3377d1cf, v48
	v_fmac_f32_e32 v44, 0x3f317217, v48
	v_cmp_lt_f32_e64 s[0:1], |v48|, s21
	v_sub_f32_e32 v1, -0.5, v1
	v_mul_f32_e32 v0, 0x3fb8aa3b, v0
	v_cndmask_b32_e64 v44, v48, v44, s[0:1]
	v_sub_f32_e32 v44, v44, v45
	v_add_f32_e32 v2, v2, v44
	v_mul_f32_e64 v44, |v3|, s87
	v_exp_f32_e32 v44, v44
	v_max_f32_e64 v3, -v3, 0
	v_add_f32_e32 v45, v54, v50
	v_mul_f32_e32 v45, 0xbfb8aa3b, v45
	v_add_f32_e32 v44, 1.0, v44
	v_cmp_gt_f32_e32 vcc, s2, v44
	v_exp_f32_e32 v45, v45
	v_sub_f32_e32 v2, -0.5, v2
	v_cndmask_b32_e64 v48, 0, 32, vcc
	v_ldexp_f32 v44, v44, v48
	v_log_f32_e32 v44, v44
	v_mul_f32_e32 v1, 0x3fb8aa3b, v1
	v_mul_f32_e32 v2, 0x3fb8aa3b, v2
	v_exp_f32_e32 v0, v0
	v_mul_f32_e32 v48, 0x3f317217, v44
	v_fma_f32 v48, v44, s20, -v48
	v_fmac_f32_e32 v48, 0x3377d1cf, v44
	v_fmac_f32_e32 v48, 0x3f317217, v44
	v_cmp_lt_f32_e64 s[0:1], |v44|, s21
	v_exp_f32_e32 v1, v1
	v_exp_f32_e32 v2, v2
	v_cndmask_b32_e64 v44, v44, v48, s[0:1]
	v_cndmask_b32_e32 v48, 0, v197, vcc
	v_sub_f32_e32 v44, v44, v48
	v_add_f32_e32 v3, v3, v44
	v_add_f32_e32 v44, v55, v51
	v_mul_f32_e32 v44, 0xbfb8aa3b, v44
	v_exp_f32_e32 v44, v44
	v_sub_f32_e32 v3, -0.5, v3
	v_mul_f32_e32 v3, 0x3fb8aa3b, v3
	v_exp_f32_e32 v3, v3
	v_add_f32_e32 v45, 1.0, v45
	v_add_f32_e32 v44, 1.0, v44
	v_rcp_f32_e32 v156, v45
	v_rcp_f32_e32 v157, v44
	v_lshlrev_b32_e32 v72, 16, v73
	v_and_b32_e32 v73, 0xffff0000, v73
	v_mul_f32_e32 v0, 0xbfb8aa3b, v0
	v_mul_f32_e32 v1, 0xbfb8aa3b, v1
	v_mul_f32_e32 v2, 0xbfb8aa3b, v2
	v_mul_f32_e32 v3, 0xbfb8aa3b, v3
	v_pk_add_f32 v[44:45], v[58:59], v[72:73] neg_lo:[0,1] neg_hi:[0,1]
	v_lshlrev_b32_e32 v82, 16, v70
	v_and_b32_e32 v83, 0xffff0000, v70
	v_exp_f32_e32 v0, v0
	v_exp_f32_e32 v1, v1
	v_exp_f32_e32 v2, v2
	v_exp_f32_e32 v3, v3
	v_pk_fma_f32 v[170:171], v[46:47], v[44:45], v[72:73]
	v_pk_add_f32 v[44:45], v[156:157], -1.0 op_sel_hi:[1,0]
	v_lshlrev_b32_e32 v70, 16, v71
	v_pk_fma_f32 v[42:43], v[42:43], v[44:45], 1.0 op_sel_hi:[1,1,0]
	s_waitcnt vmcnt(0)
	v_sub_f32_e32 v45, v61, v83
	v_sub_f32_e32 v44, v60, v82
	v_and_b32_e32 v71, 0xffff0000, v71
	s_waitcnt lgkmcnt(0)
	v_pk_fma_f32 v[36:37], v[36:37], v[44:45], v[82:83]
	v_lshlrev_b32_e32 v44, 2, v64
	v_mov_b32_e32 v45, v65
	v_sub_f32_e32 v47, v63, v71
	v_sub_f32_e32 v46, v62, v70
	v_lshl_add_u64 v[154:155], v[80:81], 0, v[44:45]
	v_pk_mul_f32 v[40:41], v[40:41], v[168:169]
	v_pk_mul_f32 v[42:43], v[42:43], v[170:171]
	v_pk_fma_f32 v[38:39], v[38:39], v[46:47], v[70:71]
	s_nop 0
	v_accvgpr_write_b32 a0, v0
	v_accvgpr_write_b32 a1, v1
	v_accvgpr_write_b32 a2, v2
	v_accvgpr_write_b32 a3, v3
	v_accvgpr_write_b32 a4, v40
	v_accvgpr_write_b32 a5, v41
	v_accvgpr_write_b32 a6, v42
	v_accvgpr_write_b32 a7, v43
	v_accvgpr_write_b32 a8, v36
	v_accvgpr_write_b32 a9, v37
	v_accvgpr_write_b32 a10, v38
	v_accvgpr_write_b32 a11, v39
	global_load_dwordx4 v[36:39], v[74:75], off offset:2048
	s_nop 0
	global_load_dwordx4 v[44:47], v[76:77], off offset:2048
	global_load_dwordx4 v[48:51], v[74:75], off offset:2112
	global_load_dwordx4 v[56:59], v[76:77], off offset:2112
	s_waitcnt vmcnt(3)
	v_mfma_f32_16x16x32_bf16 v[36:39], v[36:39], v[32:35], 0
	s_waitcnt vmcnt(2)
	v_mfma_f32_16x16x32_bf16 v[78:81], v[44:47], v[28:31], 0
	s_waitcnt vmcnt(1)
	v_mfma_f32_16x16x32_bf16 v[36:39], v[48:51], v[24:27], v[36:39]
	ds_read_b128 v[90:93], v208 offset:8256
	ds_read_b128 v[74:77], v208 offset:8512
	ds_read_b128 v[48:51], v208 offset:8768
	ds_read_b128 v[60:63], v208 offset:9024
	ds_read_b128 v[44:47], v208 offset:9280
	ds_read_b128 v[52:55], v208 offset:9536
	ds_read_b128 v[70:73], v208 offset:9792
	ds_read_b128 v[66:69], v208 offset:10048
	s_waitcnt vmcnt(0)
	v_mfma_f32_16x16x32_bf16 v[78:81], v[56:59], v[20:23], v[78:81]
	s_and_saveexec_b64 s[0:1], s[40:41]
	s_xor_b64 s[0:1], exec, s[0:1]
	s_cbranch_execz .LBB0_458
	v_lshl_add_u64 v[56:57], v[64:65], 0, v[150:151]
	v_lshl_add_u64 v[86:87], v[56:57], 2, v[158:159]
	global_load_dwordx4 v[56:59], v[86:87], off offset:64
	global_load_dwordx4 v[82:85], v[86:87], off offset:2112
	v_add_co_u32_e32 v86, vcc, 0x1000, v86
	s_nop 1
	v_addc_co_u32_e32 v87, vcc, 0, v87, vcc
	global_load_dwordx4 v[86:89], v[86:87], off offset:64

.LBB0_462:
	s_or_b64 exec, exec, s[0:1]
	s_waitcnt lgkmcnt(7)
	v_add_f32_e32 v36, v36, v90
	v_max_f32_e64 v90, -v36, 0
	v_mul_f32_e64 v36, |v36|, s87
	v_exp_f32_e32 v36, v36
	s_waitcnt lgkmcnt(6)
	v_add_f32_e32 v74, v78, v74
	v_mul_f32_e32 v74, 0xbfb8aa3b, v74
	v_exp_f32_e32 v74, v74
	v_add_f32_e32 v36, 1.0, v36
	v_cmp_gt_f32_e32 vcc, s2, v36
	v_add_f32_e32 v37, v37, v91
	v_add_f32_e32 v74, 1.0, v74
	v_cndmask_b32_e64 v102, 0, 32, vcc
	v_ldexp_f32 v36, v36, v102
	v_log_f32_e32 v36, v36
	v_rcp_f32_e32 v166, v74
	v_max_f32_e64 v74, -v37, 0
	v_mul_f32_e64 v37, |v37|, s87
	v_exp_f32_e32 v37, v37
	v_mul_f32_e32 v102, 0x3f317217, v36
	s_mov_b32 s20, 0x3f317217
	v_fma_f32 v102, v36, s20, -v102
	v_fmac_f32_e32 v102, 0x3377d1cf, v36
	s_mov_b32 s21, 0x7f800000
	v_fmac_f32_e32 v102, 0x3f317217, v36
	v_cmp_lt_f32_e64 s[0:1], |v36|, s21
	v_add_f32_e32 v37, 1.0, v37
	v_lshlrev_b32_e32 v100, 16, v94
	v_cndmask_b32_e64 v36, v36, v102, s[0:1]
	v_cndmask_b32_e32 v102, 0, v197, vcc
	v_cmp_gt_f32_e32 vcc, s2, v37
	v_and_b32_e32 v101, 0xffff0000, v94
	v_add_f32_e32 v38, v38, v92
	v_cndmask_b32_e64 v78, 0, 32, vcc
	v_ldexp_f32 v37, v37, v78
	v_log_f32_e32 v37, v37
	v_add_f32_e32 v39, v39, v93
	v_sub_f32_e32 v36, v36, v102
	v_add_f32_e32 v36, v90, v36
	v_mul_f32_e32 v78, 0x3f317217, v37
	v_fma_f32 v78, v37, s20, -v78
	v_fmac_f32_e32 v78, 0x3377d1cf, v37
	v_fmac_f32_e32 v78, 0x3f317217, v37
	v_cmp_lt_f32_e64 s[0:1], |v37|, s21
	v_sub_f32_e32 v36, -0.5, v36
	v_mul_f32_e32 v36, 0x3fb8aa3b, v36
	v_cndmask_b32_e64 v37, v37, v78, s[0:1]
	v_cndmask_b32_e32 v78, 0, v197, vcc
	v_sub_f32_e32 v37, v37, v78
	v_add_f32_e32 v37, v74, v37
	v_add_f32_e32 v74, v79, v75
	v_mul_f32_e32 v74, 0xbfb8aa3b, v74
	v_exp_f32_e32 v74, v74
	v_sub_f32_e32 v37, -0.5, v37
	v_mul_f32_e32 v37, 0x3fb8aa3b, v37
	v_exp_f32_e32 v36, v36
	v_add_f32_e32 v74, 1.0, v74
	v_rcp_f32_e32 v167, v74
	s_waitcnt vmcnt(1)
	v_pk_add_f32 v[74:75], v[82:83], v[100:101] neg_lo:[0,1] neg_hi:[0,1]
	v_exp_f32_e32 v37, v37
	s_waitcnt lgkmcnt(1)
	v_pk_fma_f32 v[174:175], v[70:71], v[74:75], v[100:101]
	v_pk_add_f32 v[70:71], v[166:167], -1.0 op_sel_hi:[1,0]
	v_lshlrev_b32_e32 v209, 6, v98
	v_pk_fma_f32 v[60:61], v[60:61], v[70:71], 1.0 op_sel_hi:[1,1,0]
	v_max_f32_e64 v70, -v38, 0
	v_mul_f32_e64 v38, |v38|, s87
	v_exp_f32_e32 v38, v38
	v_lshlrev_b32_e32 v98, 16, v95
	v_and_b32_e32 v99, 0xffff0000, v95
	v_mul_f32_e32 v36, 0xbfb8aa3b, v36
	v_add_f32_e32 v38, 1.0, v38
	v_cmp_gt_f32_e32 vcc, s2, v38
	v_mul_f32_e32 v37, 0xbfb8aa3b, v37
	v_exp_f32_e32 v36, v36
	v_cndmask_b32_e64 v71, 0, 32, vcc
	v_ldexp_f32 v38, v38, v71
	v_log_f32_e32 v38, v38
	v_exp_f32_e32 v37, v37
	v_lshlrev_b32_e32 v94, 16, v96
	v_and_b32_e32 v95, 0xffff0000, v96
	v_mul_f32_e32 v71, 0x3f317217, v38
	v_fma_f32 v71, v38, s20, -v71
	v_fmac_f32_e32 v71, 0x3377d1cf, v38
	v_fmac_f32_e32 v71, 0x3f317217, v38
	v_cmp_lt_f32_e64 s[0:1], |v38|, s21
	v_lshlrev_b32_e32 v96, 16, v97
	v_and_b32_e32 v97, 0xffff0000, v97
	v_cndmask_b32_e64 v38, v38, v71, s[0:1]
	v_cndmask_b32_e32 v71, 0, v197, vcc
	v_sub_f32_e32 v38, v38, v71
	v_add_f32_e32 v38, v70, v38
	v_add_f32_e32 v70, v80, v76
	v_mul_f32_e32 v70, 0xbfb8aa3b, v70
	v_exp_f32_e32 v70, v70
	v_sub_f32_e32 v38, -0.5, v38
	v_mul_f32_e32 v38, 0x3fb8aa3b, v38
	v_exp_f32_e32 v38, v38
	v_add_f32_e32 v70, 1.0, v70
	v_rcp_f32_e32 v172, v70
	v_max_f32_e64 v70, -v39, 0
	v_mul_f32_e64 v39, |v39|, s87
	v_exp_f32_e32 v39, v39
	v_mul_f32_e32 v38, 0xbfb8aa3b, v38
	v_exp_f32_e32 v38, v38
	v_pk_mul_f32 v[60:61], v[60:61], v[174:175]
	v_add_f32_e32 v39, 1.0, v39
	v_cmp_gt_f32_e32 vcc, s2, v39
	s_nop 1
	v_cndmask_b32_e64 v71, 0, 32, vcc
	v_ldexp_f32 v39, v39, v71
	v_log_f32_e32 v39, v39
	s_nop 0
	v_mul_f32_e32 v71, 0x3f317217, v39
	v_fma_f32 v71, v39, s20, -v71
	v_fmac_f32_e32 v71, 0x3377d1cf, v39
	v_fmac_f32_e32 v71, 0x3f317217, v39
	v_cmp_lt_f32_e64 s[0:1], |v39|, s21
	s_nop 1
	v_cndmask_b32_e64 v39, v39, v71, s[0:1]
	v_cndmask_b32_e32 v71, 0, v197, vcc
	v_sub_f32_e32 v39, v39, v71
	v_add_f32_e32 v39, v70, v39
	v_add_f32_e32 v70, v81, v77
	v_mul_f32_e32 v70, 0xbfb8aa3b, v70
	v_exp_f32_e32 v70, v70
	v_sub_f32_e32 v39, -0.5, v39
	v_mul_f32_e32 v39, 0x3fb8aa3b, v39
	v_exp_f32_e32 v39, v39
	v_add_f32_e32 v70, 1.0, v70
	v_rcp_f32_e32 v173, v70
	v_pk_add_f32 v[70:71], v[84:85], v[98:99] neg_lo:[0,1] neg_hi:[0,1]
	v_mul_f32_e32 v39, 0xbfb8aa3b, v39
	v_exp_f32_e32 v39, v39
	v_pk_fma_f32 v[180:181], v[72:73], v[70:71], v[98:99]
	v_pk_add_f32 v[70:71], v[172:173], -1.0 op_sel_hi:[1,0]
	s_waitcnt vmcnt(0)
	v_sub_f32_e32 v73, v89, v97
	v_pk_fma_f32 v[62:63], v[62:63], v[70:71], 1.0 op_sel_hi:[1,1,0]
	v_sub_f32_e32 v71, v87, v95
	v_sub_f32_e32 v70, v86, v94
	v_sub_f32_e32 v72, v88, v96
	s_waitcnt lgkmcnt(0)
	v_pk_fma_f32 v[66:67], v[66:67], v[70:71], v[94:95]
	v_pk_mul_f32 v[62:63], v[62:63], v[180:181]
	v_pk_fma_f32 v[68:69], v[68:69], v[72:73], v[96:97]
	s_nop 0
	v_accvgpr_write_b32 a12, v36
	v_accvgpr_write_b32 a13, v37
	v_accvgpr_write_b32 a14, v38
	v_accvgpr_write_b32 a15, v39
	v_accvgpr_write_b32 a16, v60
	v_accvgpr_write_b32 a17, v61
	v_accvgpr_write_b32 a18, v62
	v_accvgpr_write_b32 a19, v63
	v_accvgpr_write_b32 a20, v66
	v_accvgpr_write_b32 a21, v67
	v_accvgpr_write_b32 a22, v68
	v_accvgpr_write_b32 a23, v69
	s_nop 1
	v_lshl_or_b32 v66, v209, 1, v198
	v_mov_b32_e32 v67, v65
	v_lshl_add_u64 v[74:75], v[160:161], 0, v[66:67]
	v_lshl_add_u64 v[78:79], v[162:163], 0, v[66:67]
	global_load_dwordx4 v[66:69], v[74:75], off
	global_load_dwordx4 v[70:73], v[78:79], off
	s_nop 0
	global_load_dwordx4 v[74:77], v[74:75], off offset:64
	s_nop 0
	global_load_dwordx4 v[78:81], v[78:79], off offset:64
	s_waitcnt vmcnt(3)
	v_mfma_f32_16x16x32_bf16 v[66:69], v[66:69], v[32:35], 0
	s_waitcnt vmcnt(2)
	v_mfma_f32_16x16x32_bf16 v[70:73], v[70:73], v[28:31], 0
	s_waitcnt vmcnt(1)
	v_mfma_f32_16x16x32_bf16 v[66:69], v[74:77], v[24:27], v[66:69]
	s_waitcnt vmcnt(0)
	v_mfma_f32_16x16x32_bf16 v[98:101], v[78:81], v[20:23], v[70:73]
	ds_read_b128 v[110:113], v208 offset:8320
	ds_read_b128 v[102:105], v208 offset:8576
	ds_read_b128 v[74:77], v208 offset:8832
	ds_read_b128 v[90:93], v208 offset:9088
	ds_read_b128 v[70:73], v208 offset:9344
	ds_read_b128 v[78:81], v208 offset:9600
	ds_read_b128 v[94:97], v208 offset:9856
	ds_read_b128 v[86:89], v208 offset:10112
	s_and_saveexec_b64 s[0:1], s[40:41]
	s_xor_b64 s[0:1], exec, s[0:1]
	s_cbranch_execz .LBB0_464
	v_lshl_add_u64 v[82:83], v[64:65], 0, v[150:151]
	v_lshl_add_u64 v[114:115], v[82:83], 2, v[158:159]
	global_load_dwordx4 v[82:85], v[114:115], off offset:128
	global_load_dwordx4 v[106:109], v[114:115], off offset:2176
	v_add_co_u32_e32 v114, vcc, 0x1000, v114
	s_nop 1
	v_addc_co_u32_e32 v115, vcc, 0, v115, vcc
	global_load_dwordx4 v[114:117], v[114:115], off offset:128

.LBB0_468:
	s_or_b64 exec, exec, s[0:1]
	s_waitcnt lgkmcnt(7)
	v_add_f32_e32 v66, v66, v110
	v_mul_f32_e64 v110, |v66|, s87
	v_exp_f32_e32 v110, v110
	s_mov_b32 s20, 0x3f317217
	s_mov_b32 s21, 0x7f800000
	v_max_f32_e64 v66, -v66, 0
	v_add_f32_e32 v110, 1.0, v110
	v_cmp_gt_f32_e32 vcc, s2, v110
	v_add_f32_e32 v67, v67, v111
	s_waitcnt lgkmcnt(6)
	v_add_f32_e32 v98, v98, v102
	v_cndmask_b32_e64 v124, 0, 32, vcc
	v_ldexp_f32 v110, v110, v124
	v_log_f32_e32 v110, v110
	v_mul_f32_e32 v98, 0xbfb8aa3b, v98
	v_add_f32_e32 v99, v99, v103
	v_exp_f32_e32 v98, v98
	v_mul_f32_e32 v124, 0x3f317217, v110
	v_fma_f32 v124, v110, s20, -v124
	v_fmac_f32_e32 v124, 0x3377d1cf, v110
	v_fmac_f32_e32 v124, 0x3f317217, v110
	v_cmp_lt_f32_e64 s[0:1], |v110|, s21
	v_mul_f32_e32 v99, 0xbfb8aa3b, v99
	v_exp_f32_e32 v99, v99
	v_cndmask_b32_e64 v110, v110, v124, s[0:1]
	v_cndmask_b32_e32 v124, 0, v197, vcc
	v_sub_f32_e32 v110, v110, v124
	v_add_f32_e32 v66, v66, v110
	v_mul_f32_e64 v110, |v67|, s87
	v_exp_f32_e32 v110, v110
	v_add_f32_e32 v98, 1.0, v98
	v_rcp_f32_e32 v176, v98
	v_add_f32_e32 v98, 1.0, v99
	v_add_f32_e32 v102, 1.0, v110
	v_cmp_gt_f32_e32 vcc, s2, v102
	v_add_f32_e32 v68, v68, v112
	v_max_f32_e64 v67, -v67, 0
	v_cndmask_b32_e64 v110, 0, 32, vcc
	v_ldexp_f32 v102, v102, v110
	v_log_f32_e32 v102, v102
	v_rcp_f32_e32 v177, v98
	v_mul_f32_e64 v98, |v68|, s87
	v_lshlrev_b32_e32 v122, 16, v120
	v_mul_f32_e32 v110, 0x3f317217, v102
	v_fma_f32 v110, v102, s20, -v110
	v_fmac_f32_e32 v110, 0x3377d1cf, v102
	v_fmac_f32_e32 v110, 0x3f317217, v102
	v_cmp_lt_f32_e64 s[0:1], |v102|, s21
	v_and_b32_e32 v123, 0xffff0000, v120
	v_max_f32_e64 v68, -v68, 0
	v_cndmask_b32_e64 v102, v102, v110, s[0:1]
	v_cndmask_b32_e32 v110, 0, v197, vcc
	v_sub_f32_e32 v102, v102, v110
	v_add_f32_e32 v67, v67, v102
	v_exp_f32_e32 v102, v98
	s_waitcnt vmcnt(1)
	v_pk_add_f32 v[98:99], v[106:107], v[122:123] neg_lo:[0,1] neg_hi:[0,1]
	v_add_f32_e32 v69, v69, v113
	s_waitcnt lgkmcnt(1)
	v_pk_fma_f32 v[182:183], v[94:95], v[98:99], v[122:123]
	v_add_f32_e32 v98, 1.0, v102
	v_cmp_gt_f32_e32 vcc, s2, v98
	v_pk_add_f32 v[94:95], v[176:177], -1.0 op_sel_hi:[1,0]
	v_sub_f32_e32 v66, -0.5, v66
	v_cndmask_b32_e64 v99, 0, 32, vcc
	v_ldexp_f32 v98, v98, v99
	v_log_f32_e32 v98, v98
	v_pk_fma_f32 v[90:91], v[90:91], v[94:95], 1.0 op_sel_hi:[1,1,0]
	v_sub_f32_e32 v67, -0.5, v67
	v_pk_mul_f32 v[122:123], v[90:91], v[182:183]
	v_mul_f32_e32 v90, 0x3f317217, v98
	v_fma_f32 v90, v98, s20, -v90
	v_fmac_f32_e32 v90, 0x3377d1cf, v98
	v_fmac_f32_e32 v90, 0x3f317217, v98
	v_cmp_lt_f32_e64 s[0:1], |v98|, s21
	v_cndmask_b32_e32 v91, 0, v197, vcc
	v_mul_f32_e32 v66, 0x3fb8aa3b, v66
	v_cndmask_b32_e64 v90, v98, v90, s[0:1]
	v_sub_f32_e32 v90, v90, v91
	v_add_f32_e32 v68, v68, v90
	v_mul_f32_e64 v90, |v69|, s87
	v_exp_f32_e32 v90, v90
	v_max_f32_e64 v69, -v69, 0
	v_add_f32_e32 v91, v100, v104
	v_mul_f32_e32 v91, 0xbfb8aa3b, v91
	v_add_f32_e32 v90, 1.0, v90
	v_cmp_gt_f32_e32 vcc, s2, v90
	v_exp_f32_e32 v91, v91
	v_sub_f32_e32 v68, -0.5, v68
	v_cndmask_b32_e64 v94, 0, 32, vcc
	v_ldexp_f32 v90, v90, v94
	v_log_f32_e32 v90, v90
	v_mul_f32_e32 v67, 0x3fb8aa3b, v67
	v_mul_f32_e32 v68, 0x3fb8aa3b, v68
	v_exp_f32_e32 v66, v66
	v_mul_f32_e32 v94, 0x3f317217, v90
	v_fma_f32 v94, v90, s20, -v94
	v_fmac_f32_e32 v94, 0x3377d1cf, v90
	v_fmac_f32_e32 v94, 0x3f317217, v90
	v_cmp_lt_f32_e64 s[0:1], |v90|, s21
	v_exp_f32_e32 v67, v67
	v_exp_f32_e32 v68, v68
	v_cndmask_b32_e64 v90, v90, v94, s[0:1]
	v_cndmask_b32_e32 v94, 0, v197, vcc
	v_sub_f32_e32 v90, v90, v94
	v_add_f32_e32 v69, v69, v90
	v_add_f32_e32 v90, v101, v105
	v_mul_f32_e32 v90, 0xbfb8aa3b, v90
	v_exp_f32_e32 v90, v90
	v_sub_f32_e32 v69, -0.5, v69
	v_mul_f32_e32 v69, 0x3fb8aa3b, v69
	v_exp_f32_e32 v69, v69
	v_add_f32_e32 v91, 1.0, v91
	v_add_f32_e32 v90, 1.0, v90
	v_rcp_f32_e32 v178, v91
	v_rcp_f32_e32 v179, v90
	v_lshlrev_b32_e32 v120, 16, v121
	v_and_b32_e32 v121, 0xffff0000, v121
	v_mul_f32_e32 v66, 0xbfb8aa3b, v66
	v_mul_f32_e32 v67, 0xbfb8aa3b, v67
	v_mul_f32_e32 v68, 0xbfb8aa3b, v68
	v_mul_f32_e32 v69, 0xbfb8aa3b, v69
	v_pk_add_f32 v[90:91], v[108:109], v[120:121] neg_lo:[0,1] neg_hi:[0,1]
	v_exp_f32_e32 v66, v66
	v_exp_f32_e32 v67, v67
	v_exp_f32_e32 v68, v68
	v_exp_f32_e32 v69, v69
	v_pk_fma_f32 v[184:185], v[96:97], v[90:91], v[120:121]
	v_pk_add_f32 v[90:91], v[178:179], -1.0 op_sel_hi:[1,0]
	v_lshlrev_b32_e32 v210, 16, v118
	v_and_b32_e32 v211, 0xffff0000, v118
	v_pk_fma_f32 v[90:91], v[92:93], v[90:91], 1.0 op_sel_hi:[1,1,0]
	v_lshlrev_b32_e32 v118, 16, v119
	v_and_b32_e32 v119, 0xffff0000, v119
	v_pk_mul_f32 v[124:125], v[90:91], v[184:185]
	s_waitcnt vmcnt(0)
	v_sub_f32_e32 v91, v115, v211
	v_sub_f32_e32 v90, v114, v210
	v_sub_f32_e32 v93, v117, v119
	v_sub_f32_e32 v92, v116, v118
	s_waitcnt lgkmcnt(0)
	v_pk_fma_f32 v[86:87], v[86:87], v[90:91], v[210:211]
	v_lshl_or_b32 v90, v209, 1, v199
	v_mov_b32_e32 v91, v65
	v_pk_fma_f32 v[88:89], v[88:89], v[92:93], v[118:119]
	s_nop 0
	v_accvgpr_write_b32 a24, v66
	v_accvgpr_write_b32 a25, v67
	v_accvgpr_write_b32 a26, v68
	v_accvgpr_write_b32 a27, v69
	v_accvgpr_write_b32 a28, v122
	v_accvgpr_write_b32 a29, v123
	v_accvgpr_write_b32 a30, v124
	v_accvgpr_write_b32 a31, v125
	v_accvgpr_write_b32 a32, v86
	v_accvgpr_write_b32 a33, v87
	v_accvgpr_write_b32 a34, v88
	v_accvgpr_write_b32 a35, v89
	v_lshl_add_u64 v[94:95], v[160:161], 0, v[90:91]
	global_load_dwordx4 v[86:89], v[94:95], off
	v_lshl_add_u64 v[98:99], v[162:163], 0, v[90:91]
	global_load_dwordx4 v[90:93], v[98:99], off
	s_nop 0
	global_load_dwordx4 v[94:97], v[94:95], off offset:64
	s_waitcnt vmcnt(1)
	v_mfma_f32_16x16x32_bf16 v[106:109], v[90:93], v[28:31], 0
	global_load_dwordx4 v[98:101], v[98:99], off offset:64
	v_mfma_f32_16x16x32_bf16 v[32:35], v[86:89], v[32:35], 0
	s_waitcnt vmcnt(1)
	v_mfma_f32_16x16x32_bf16 v[114:117], v[94:97], v[24:27], v[32:35]
	ds_read_b128 v[118:121], v208 offset:8384
	ds_read_b128 v[102:105], v208 offset:8640
	ds_read_b128 v[86:89], v208 offset:8896
	ds_read_b128 v[90:93], v208 offset:9152
	ds_read_b128 v[28:31], v208 offset:9408
	s_nop 0
	ds_read_b128 v[32:35], v208 offset:9664
	ds_read_b128 v[94:97], v208 offset:9920
	ds_read_b128 v[24:27], v208 offset:10176
	s_waitcnt vmcnt(0)
	v_mfma_f32_16x16x32_bf16 v[106:109], v[98:101], v[20:23], v[106:109]
	s_and_saveexec_b64 s[0:1], s[40:41]
	s_xor_b64 s[0:1], exec, s[0:1]
	s_cbranch_execz .LBB0_470
	v_lshl_add_u64 v[20:21], v[64:65], 0, v[150:151]
	v_lshl_add_u64 v[98:99], v[20:21], 2, v[158:159]
	global_load_dwordx4 v[20:23], v[98:99], off offset:192
	global_load_dwordx4 v[110:113], v[98:99], off offset:2240
	v_add_co_u32_e32 v98, vcc, 0x1000, v98
	s_nop 1
	v_addc_co_u32_e32 v99, vcc, 0, v99, vcc
	global_load_dwordx4 v[98:101], v[98:99], off offset:192

.LBB0_474:
	s_or_b64 exec, exec, s[0:1]
	v_lshlrev_b32_e32 v150, 16, v146
	v_and_b32_e32 v151, 0xffff0000, v146
	v_pk_add_f32 v[16:17], v[16:17], v[150:151] neg_lo:[0,1] neg_hi:[0,1]
	v_pk_mul_f32 v[8:9], v[8:9], v[168:169]
	v_pk_fma_f32 v[12:13], v[12:13], v[16:17], v[150:151]
	v_lshlrev_b32_e32 v158, 16, v147
	v_pk_mul_f32 v[16:17], v[12:13], v[40:41]
	v_and_b32_e32 v159, 0xffff0000, v147
	v_fma_f32 v64, v4, v16, 0
	v_mul_f32_e32 v4, v152, v8
	v_fma_f32 v160, v12, v4, 0
	v_add_f32_e32 v4, 0, v16
	v_fmac_f32_e32 v64, v5, v17
	v_mul_f32_e32 v5, v153, v9
	v_fmac_f32_e32 v160, v13, v5
	v_add_f32_e32 v40, v17, v4
	v_pk_add_f32 v[4:5], v[18:19], v[158:159] neg_lo:[0,1] neg_hi:[0,1]
	v_pk_mul_f32 v[16:17], v[10:11], v[170:171]
	v_pk_fma_f32 v[14:15], v[14:15], v[4:5], v[158:159]
	v_pk_mul_f32 v[18:19], v[48:49], v[174:175]
	v_pk_mul_f32 v[4:5], v[14:15], v[42:43]
	v_mul_f32_e32 v41, v166, v18
	v_fmac_f32_e32 v64, v6, v4
	v_add_f32_e32 v4, v4, v40
	v_fmac_f32_e32 v64, v7, v5
	v_add_f32_e32 v40, v5, v4
	v_lshlrev_b32_e32 v4, 16, v144
	v_and_b32_e32 v5, 0xffff0000, v144
	v_pk_add_f32 v[10:11], v[56:57], v[4:5] neg_lo:[0,1] neg_hi:[0,1]
	v_mul_f32_e32 v6, v156, v16
	v_pk_fma_f32 v[10:11], v[52:53], v[10:11], v[4:5]
	v_fmac_f32_e32 v160, v14, v6
	v_mul_f32_e32 v6, v157, v17
	v_pk_mul_f32 v[4:5], v[10:11], v[60:61]
	v_fmac_f32_e32 v160, v15, v6
	v_lshlrev_b32_e32 v6, 16, v145
	v_and_b32_e32 v7, 0xffff0000, v145
	v_fmac_f32_e32 v64, v44, v4
	v_add_f32_e32 v4, v40, v4
	v_fmac_f32_e32 v160, v10, v41
	v_fmac_f32_e32 v64, v45, v5
	v_mul_f32_e32 v40, v167, v19
	v_add_f32_e32 v42, v5, v4
	v_pk_add_f32 v[4:5], v[58:59], v[6:7] neg_lo:[0,1] neg_hi:[0,1]
	v_fmac_f32_e32 v160, v11, v40
	v_pk_fma_f32 v[40:41], v[54:55], v[4:5], v[6:7]
	v_pk_mul_f32 v[44:45], v[50:51], v[180:181]
	v_pk_mul_f32 v[4:5], v[40:41], v[62:63]
	v_mul_f32_e32 v6, v172, v44
	v_fmac_f32_e32 v64, v46, v4
	v_add_f32_e32 v4, v4, v42
	v_fmac_f32_e32 v64, v47, v5
	v_add_f32_e32 v48, v5, v4
	v_lshlrev_b32_e32 v4, 16, v142
	v_and_b32_e32 v5, 0xffff0000, v142
	v_pk_add_f32 v[42:43], v[82:83], v[4:5] neg_lo:[0,1] neg_hi:[0,1]
	v_fmac_f32_e32 v160, v40, v6
	v_pk_fma_f32 v[42:43], v[78:79], v[42:43], v[4:5]
	v_mul_f32_e32 v6, v173, v45
	v_pk_mul_f32 v[46:47], v[74:75], v[182:183]
	v_pk_mul_f32 v[4:5], v[42:43], v[122:123]
	v_fmac_f32_e32 v160, v41, v6
	v_lshlrev_b32_e32 v6, 16, v143
	v_and_b32_e32 v7, 0xffff0000, v143
	v_fmac_f32_e32 v64, v70, v4
	v_mul_f32_e32 v49, v176, v46
	v_add_f32_e32 v4, v48, v4
	v_fmac_f32_e32 v160, v42, v49
	v_fmac_f32_e32 v64, v71, v5
	v_mul_f32_e32 v48, v177, v47
	v_add_f32_e32 v52, v5, v4
	v_pk_add_f32 v[4:5], v[84:85], v[6:7] neg_lo:[0,1] neg_hi:[0,1]
	v_fmac_f32_e32 v160, v43, v48
	v_pk_fma_f32 v[48:49], v[80:81], v[4:5], v[6:7]
	s_mov_b32 s20, 0x3f317217
	v_pk_mul_f32 v[4:5], v[48:49], v[124:125]
	s_mov_b32 s21, 0x7f800000
	v_fmac_f32_e32 v64, v72, v4
	v_add_f32_e32 v4, v4, v52
	v_add_f32_e32 v82, v5, v4
	s_waitcnt lgkmcnt(7)
	v_add_f32_e32 v4, v114, v118
	v_fmac_f32_e32 v64, v73, v5
	v_mul_f32_e64 v5, |v4|, s87
	v_exp_f32_e32 v5, v5
	v_max_f32_e64 v4, -v4, 0
	s_waitcnt lgkmcnt(6)
	v_add_f32_e32 v53, v106, v102
	v_mul_f32_e32 v53, 0xbfb8aa3b, v53
	v_add_f32_e32 v5, 1.0, v5
	v_cmp_gt_f32_e32 vcc, s2, v5
	v_exp_f32_e32 v53, v53
	v_pk_mul_f32 v[50:51], v[76:77], v[184:185]
	v_cndmask_b32_e64 v52, 0, 32, vcc
	v_ldexp_f32 v5, v5, v52
	v_log_f32_e32 v5, v5
	v_mul_f32_e32 v6, v178, v50
	v_lshlrev_b32_e32 v54, 16, v138
	v_and_b32_e32 v55, 0xffff0000, v138
	v_mul_f32_e32 v52, 0x3f317217, v5
	v_fma_f32 v52, v5, s20, -v52
	v_fmac_f32_e32 v52, 0x3377d1cf, v5
	v_fmac_f32_e32 v52, 0x3f317217, v5
	v_cmp_lt_f32_e64 s[0:1], |v5|, s21
	v_fmac_f32_e32 v160, v48, v6
	v_mul_f32_e32 v6, v179, v51
	v_cndmask_b32_e64 v5, v5, v52, s[0:1]
	v_cndmask_b32_e32 v52, 0, v197, vcc
	v_sub_f32_e32 v5, v5, v52
	v_add_f32_e32 v4, v4, v5
	v_add_f32_e32 v5, v115, v119
	v_mul_f32_e64 v52, |v5|, s87
	v_exp_f32_e32 v52, v52
	v_max_f32_e64 v5, -v5, 0
	v_fmac_f32_e32 v160, v49, v6
	v_and_b32_e32 v7, 0xffff0000, v140
	v_add_f32_e32 v52, 1.0, v52
	v_cmp_gt_f32_e32 vcc, s2, v52
	v_lshlrev_b32_e32 v6, 16, v140
	s_waitcnt vmcnt(2)
	v_pk_add_f32 v[20:21], v[20:21], v[6:7] neg_lo:[0,1] neg_hi:[0,1]
	v_cndmask_b32_e64 v74, 0, 32, vcc
	v_ldexp_f32 v52, v52, v74
	v_log_f32_e32 v52, v52
	s_waitcnt lgkmcnt(2)
	v_pk_fma_f32 v[20:21], v[32:33], v[20:21], v[6:7]
	v_lshlrev_b32_e32 v76, 16, v139
	v_and_b32_e32 v77, 0xffff0000, v139
	v_mul_f32_e32 v74, 0x3f317217, v52
	v_fma_f32 v74, v52, s20, -v74
	v_fmac_f32_e32 v74, 0x3377d1cf, v52
	v_fmac_f32_e32 v74, 0x3f317217, v52
	v_cmp_lt_f32_e64 s[0:1], |v52|, s21
	v_pk_mul_f32 v[146:147], v[8:9], v[8:9]
	v_pk_mul_f32 v[150:151], v[16:17], v[16:17]
	v_cndmask_b32_e64 v52, v52, v74, s[0:1]
	v_cndmask_b32_e32 v74, 0, v197, vcc
	v_sub_f32_e32 v52, v52, v74
	v_add_f32_e32 v5, v5, v52
	v_add_f32_e32 v52, v107, v103
	v_mul_f32_e32 v52, 0xbfb8aa3b, v52
	v_exp_f32_e32 v74, v52
	v_add_f32_e32 v52, 1.0, v53
	v_rcp_f32_e32 v52, v52
	v_pk_mul_f32 v[56:57], v[18:19], v[18:19]
	v_add_f32_e32 v53, 1.0, v74
	v_rcp_f32_e32 v53, v53
	s_waitcnt vmcnt(1)
	v_pk_add_f32 v[74:75], v[110:111], v[54:55] neg_lo:[0,1] neg_hi:[0,1]
	v_pk_mul_f32 v[58:59], v[44:45], v[44:45]
	s_waitcnt lgkmcnt(1)
	v_pk_fma_f32 v[54:55], v[94:95], v[74:75], v[54:55]
	v_pk_add_f32 v[74:75], v[52:53], -1.0 op_sel_hi:[1,0]
	v_pk_mul_f32 v[60:61], v[46:47], v[46:47]
	v_pk_fma_f32 v[74:75], v[90:91], v[74:75], 1.0 op_sel_hi:[1,1,0]
	v_pk_mul_f32 v[70:71], v[50:51], v[50:51]
	v_pk_mul_f32 v[74:75], v[74:75], v[54:55]
	v_pk_mul_f32 v[54:55], v[86:87], v[54:55]
	v_pk_mul_f32 v[6:7], v[20:21], v[74:75]
	v_pk_mul_f32 v[32:33], v[52:53], v[54:55]
	v_fmac_f32_e32 v64, v28, v6
	v_add_f32_e32 v28, v116, v120
	v_add_f32_e32 v6, v82, v6
	v_mul_f32_e64 v82, |v28|, s87
	v_exp_f32_e32 v82, v82
	v_fmac_f32_e32 v64, v29, v7
	v_add_f32_e32 v87, v7, v6
	v_max_f32_e64 v6, -v28, 0
	v_add_f32_e32 v29, 1.0, v82
	v_cmp_gt_f32_e32 vcc, s2, v29
	v_pk_mul_f32 v[32:33], v[20:21], v[32:33]
	v_and_b32_e32 v79, 0xffff0000, v141
	v_cndmask_b32_e64 v82, 0, 32, vcc
	v_ldexp_f32 v29, v29, v82
	v_log_f32_e32 v29, v29
	v_cndmask_b32_e32 v28, 0, v197, vcc
	v_add_f32_e32 v32, v160, v32
	v_add_f32_e32 v86, v33, v32
	v_mul_f32_e32 v7, 0x3f317217, v29
	v_fma_f32 v7, v29, s20, -v7
	v_fmac_f32_e32 v7, 0x3377d1cf, v29
	v_fmac_f32_e32 v7, 0x3f317217, v29
	v_cmp_lt_f32_e64 s[0:1], |v29|, s21
	v_lshlrev_b32_e32 v78, 16, v141
	v_pk_mul_f32 v[80:81], v[54:55], v[54:55]
	v_cndmask_b32_e64 v7, v29, v7, s[0:1]
	v_sub_f32_e32 v7, v7, v28
	v_add_f32_e32 v6, v6, v7
	v_add_f32_e32 v7, v117, v121
	v_mul_f32_e64 v28, |v7|, s87
	v_exp_f32_e32 v28, v28
	v_max_f32_e64 v7, -v7, 0
	v_add_f32_e32 v29, v108, v104
	v_mul_f32_e32 v29, 0xbfb8aa3b, v29
	v_add_f32_e32 v28, 1.0, v28
	v_cmp_gt_f32_e32 vcc, s2, v28
	v_exp_f32_e32 v29, v29
	v_pk_add_f32 v[22:23], v[22:23], v[78:79] neg_lo:[0,1] neg_hi:[0,1]
	v_cndmask_b32_e64 v32, 0, 32, vcc
	v_ldexp_f32 v28, v28, v32
	v_log_f32_e32 v28, v28
	v_add_f32_e32 v29, 1.0, v29
	v_rcp_f32_e32 v82, v29
	v_lshlrev_b32_e32 v72, 16, v137
	v_mul_f32_e32 v32, 0x3f317217, v28
	v_fma_f32 v32, v28, s20, -v32
	v_fmac_f32_e32 v32, 0x3377d1cf, v28
	v_fmac_f32_e32 v32, 0x3f317217, v28
	v_cmp_lt_f32_e64 s[0:1], |v28|, s21
	v_and_b32_e32 v73, 0xffff0000, v137
	v_sub_f32_e32 v4, -0.5, v4
	v_cndmask_b32_e64 v28, v28, v32, s[0:1]
	v_cndmask_b32_e32 v32, 0, v197, vcc
	v_sub_f32_e32 v28, v28, v32
	v_add_f32_e32 v7, v7, v28
	v_add_f32_e32 v28, v109, v105
	v_mul_f32_e32 v28, 0xbfb8aa3b, v28
	v_exp_f32_e32 v28, v28
	v_sub_f32_e32 v5, -0.5, v5
	v_sub_f32_e32 v6, -0.5, v6
	v_sub_f32_e32 v7, -0.5, v7
	v_add_f32_e32 v28, 1.0, v28
	v_rcp_f32_e32 v83, v28
	v_pk_add_f32 v[28:29], v[112:113], v[76:77] neg_lo:[0,1] neg_hi:[0,1]
	v_mul_f32_e32 v4, 0x3fb8aa3b, v4
	v_pk_fma_f32 v[28:29], v[96:97], v[28:29], v[76:77]
	v_pk_add_f32 v[32:33], v[82:83], -1.0 op_sel_hi:[1,0]
	v_pk_mul_f32 v[84:85], v[88:89], v[28:29]
	v_pk_fma_f32 v[32:33], v[92:93], v[32:33], 1.0 op_sel_hi:[1,1,0]
	v_mul_f32_e32 v5, 0x3fb8aa3b, v5
	v_pk_mul_f32 v[76:77], v[32:33], v[28:29]
	v_add_f32_e32 v32, v146, v147
	v_add_f32_e32 v32, v150, v32
	v_add_f32_e32 v32, v151, v32
	v_add_f32_e32 v32, v32, v56
	v_add_f32_e32 v32, v57, v32
	v_add_f32_e32 v32, v58, v32
	v_add_f32_e32 v32, v59, v32
	v_add_f32_e32 v32, v32, v60
	v_add_f32_e32 v32, v61, v32
	v_add_f32_e32 v32, v70, v32
	v_add_f32_e32 v32, v71, v32
	v_add_f32_e32 v32, v32, v80
	v_pk_fma_f32 v[56:57], v[34:35], v[22:23], v[78:79]
	v_and_b32_e32 v34, 64, v192
	v_pk_mul_f32 v[28:29], v[84:85], v[84:85]
	v_add_f32_e32 v32, v81, v32
	v_xor_b32_e32 v33, 16, v192
	v_add_u32_e32 v34, 64, v34
	v_add_f32_e32 v28, v28, v32
	v_cmp_lt_i32_e32 vcc, v33, v34
	v_add_f32_e32 v32, v29, v28
	v_pk_mul_f32 v[28:29], v[82:83], v[84:85]
	v_cndmask_b32_e32 v33, v192, v33, vcc
	v_pk_mul_f32 v[28:29], v[56:57], v[28:29]
	v_lshlrev_b32_e32 v33, 2, v33
	v_pk_mul_f32 v[22:23], v[56:57], v[76:77]
	v_add_f32_e32 v28, v28, v86
	ds_bpermute_b32 v35, v33, v32
	v_fmac_f32_e32 v64, v30, v22
	v_add_f32_e32 v30, v29, v28
	s_waitcnt vmcnt(0)
	v_sub_f32_e32 v29, v101, v73
	v_sub_f32_e32 v28, v100, v72
	v_mul_f32_e32 v6, 0x3fb8aa3b, v6
	v_mul_f32_e32 v7, 0x3fb8aa3b, v7
	s_waitcnt lgkmcnt(1)
	v_pk_fma_f32 v[26:27], v[26:27], v[28:29], v[72:73]
	v_xor_b32_e32 v28, 32, v192
	v_lshlrev_b32_e32 v62, 16, v136
	v_and_b32_e32 v63, 0xffff0000, v136
	v_exp_f32_e32 v4, v4
	v_exp_f32_e32 v5, v5
	v_exp_f32_e32 v6, v6
	v_exp_f32_e32 v7, v7
	v_add_f32_e32 v22, v22, v87
	v_cmp_lt_i32_e32 vcc, v28, v34
	v_fmac_f32_e32 v64, v31, v23
	v_add_f32_e32 v31, v23, v22
	v_sub_f32_e32 v23, v99, v63
	v_sub_f32_e32 v22, v98, v62
	v_cndmask_b32_e32 v28, v192, v28, vcc
	v_pk_fma_f32 v[24:25], v[24:25], v[22:23], v[62:63]
	s_waitcnt lgkmcnt(0)
	v_add_f32_e32 v22, v32, v35
	v_lshlrev_b32_e32 v28, 2, v28
	ds_bpermute_b32 v29, v28, v22
	v_mul_f32_e32 v4, 0xbfb8aa3b, v4
	v_mul_f32_e32 v5, 0xbfb8aa3b, v5
	v_mul_f32_e32 v6, 0xbfb8aa3b, v6
	v_mul_f32_e32 v7, 0xbfb8aa3b, v7
	v_exp_f32_e32 v4, v4
	v_exp_f32_e32 v5, v5
	v_exp_f32_e32 v6, v6
	v_exp_f32_e32 v7, v7
	s_waitcnt lgkmcnt(0)
	v_add_f32_e32 v22, v22, v29
	s_mov_b32 s0, 0xf800000
	global_store_dwordx4 v[154:155], a[0:3], off nt
	global_store_dwordx4 v[154:155], a[4:7], off offset:768 nt
	global_store_dwordx4 v[154:155], a[8:11], off offset:1280 nt
	global_store_dwordx4 v[154:155], a[12:15], off offset:64 nt
	global_store_dwordx4 v[154:155], a[16:19], off offset:832 nt
	global_store_dwordx4 v[154:155], a[20:23], off offset:1344 nt
	global_store_dwordx4 v[154:155], a[24:27], off offset:128 nt
	global_store_dwordx4 v[154:155], a[28:31], off offset:896 nt
	global_store_dwordx4 v[154:155], a[32:35], off offset:1408 nt
	global_store_dwordx4 v[154:155], v[4:7], off offset:192 nt
	global_store_dwordx4 v[154:155], v[74:77], off offset:960 nt
	global_store_dwordx4 v[154:155], v[24:27], off offset:1472 nt
	v_cmp_gt_f32_e32 vcc, s0, v22
	ds_bpermute_b32 v24, v33, v30
	v_mul_f32_e32 v26, 0x4f800000, v22
	ds_bpermute_b32 v25, v33, v31
	v_cndmask_b32_e32 v22, v22, v26, vcc
	v_sqrt_f32_e32 v26, v22
	s_waitcnt lgkmcnt(1)
	v_add_f32_e32 v27, v30, v24
	ds_bpermute_b32 v23, v33, v64
	s_waitcnt lgkmcnt(1)
	v_add_f32_e32 v24, v31, v25
	v_add_u32_e32 v25, -1, v26
	v_fma_f32 v30, -v25, v26, v22
	v_cmp_ge_f32_e64 s[0:1], 0, v30
	v_add_u32_e32 v30, 1, v26
	ds_bpermute_b32 v29, v28, v27
	v_cndmask_b32_e64 v25, v26, v25, s[0:1]
	v_fma_f32 v26, -v30, v26, v22
	v_cmp_lt_f32_e64 s[0:1], 0, v26
	s_waitcnt lgkmcnt(1)
	v_add_f32_e32 v23, v64, v23
	s_waitcnt lgkmcnt(0)
	v_add_f32_e32 v27, v27, v29
	v_cndmask_b32_e64 v25, v25, v30, s[0:1]
	v_mul_f32_e32 v26, 0x37800000, v25
	v_cndmask_b32_e32 v25, v25, v26, vcc
	v_cmp_class_f32_e32 vcc, v22, v190
	ds_bpermute_b32 v26, v28, v24
	v_pk_mul_f32 v[0:1], v[0:1], v[12:13]
	v_cndmask_b32_e32 v22, v25, v22, vcc
	v_max_f32_e32 v22, 0x2b8cbccc, v22
	v_div_scale_f32 v30, s[0:1], v22, v22, 1.0
	v_rcp_f32_e32 v31, v30
	ds_bpermute_b32 v25, v28, v23
	v_pk_mul_f32 v[2:3], v[2:3], v[14:15]
	v_pk_mul_f32 v[4:5], v[4:5], v[20:21]
	v_fma_f32 v28, -v30, v31, 1.0
	v_fmac_f32_e32 v31, v28, v31
	v_div_scale_f32 v28, vcc, 1.0, v22, 1.0
	v_mul_f32_e32 v29, v28, v31
	v_fma_f32 v32, -v30, v29, v28
	v_fmac_f32_e32 v29, v32, v31
	v_fma_f32 v28, -v30, v29, v28
	v_div_fmas_f32 v28, v28, v31, v29
	v_div_fixup_f32 v58, v28, v22, 1.0
	v_mul_f32_e32 v22, v27, v58
	v_pk_mul_f32 v[28:29], v[8:9], v[58:59] op_sel_hi:[1,0]
	v_pk_mul_f32 v[30:31], v[16:17], v[58:59] op_sel_hi:[1,0]
	v_pk_fma_f32 v[0:1], v[22:23], v[28:29], v[0:1] op_sel_hi:[0,1,1] neg_lo:[1,0,0] neg_hi:[1,0,0]
	v_pk_fma_f32 v[2:3], v[22:23], v[30:31], v[2:3] op_sel_hi:[0,1,1] neg_lo:[1,0,0] neg_hi:[1,0,0]
	v_pk_mul_f32 v[32:33], v[152:153], v[28:29]
	v_pk_mul_f32 v[34:35], v[156:157], v[30:31]
	global_store_dwordx4 v[154:155], v[28:31], off offset:256 nt
	global_store_dwordx4 v[154:155], v[32:35], off offset:512 nt
	global_store_dwordx4 v[154:155], v[0:3], off offset:1024 nt
	v_pk_mul_f32 v[8:9], v[36:37], v[10:11]
	v_pk_mul_f32 v[10:11], v[38:39], v[40:41]
	v_pk_mul_f32 v[0:1], v[18:19], v[58:59] op_sel_hi:[1,0]
	v_pk_mul_f32 v[2:3], v[44:45], v[58:59] op_sel_hi:[1,0]
	v_pk_mul_f32 v[12:13], v[166:167], v[0:1]
	v_pk_mul_f32 v[14:15], v[172:173], v[2:3]
	global_store_dwordx4 v[154:155], v[0:3], off offset:320 nt
	global_store_dwordx4 v[154:155], v[12:15], off offset:576 nt
	v_pk_mul_f32 v[6:7], v[6:7], v[56:57]
	v_pk_fma_f32 v[2:3], v[22:23], v[2:3], v[10:11] op_sel_hi:[0,1,1] neg_lo:[1,0,0] neg_hi:[1,0,0]
	v_pk_fma_f32 v[0:1], v[22:23], v[0:1], v[8:9] op_sel_hi:[0,1,1] neg_lo:[1,0,0] neg_hi:[1,0,0]
	global_store_dwordx4 v[154:155], v[0:3], off offset:1088 nt
	s_mov_b32 s82, 0x800000
	v_cmp_eq_u32_e32 vcc, 0, v207
	v_pk_mul_f32 v[0:1], v[46:47], v[58:59] op_sel_hi:[1,0]
	v_pk_mul_f32 v[2:3], v[50:51], v[58:59] op_sel_hi:[1,0]
	v_pk_mul_f32 v[8:9], v[176:177], v[0:1]
	v_pk_mul_f32 v[10:11], v[178:179], v[2:3]
	global_store_dwordx4 v[154:155], v[0:3], off offset:384 nt
	global_store_dwordx4 v[154:155], v[8:11], off offset:640 nt
	s_nop 1
	v_pk_mul_f32 v[8:9], v[66:67], v[42:43]
	v_pk_mul_f32 v[10:11], v[68:69], v[48:49]
	v_pk_fma_f32 v[0:1], v[22:23], v[0:1], v[8:9] op_sel_hi:[0,1,1] neg_lo:[1,0,0] neg_hi:[1,0,0]
	v_pk_fma_f32 v[2:3], v[22:23], v[2:3], v[10:11] op_sel_hi:[0,1,1] neg_lo:[1,0,0] neg_hi:[1,0,0]
	global_store_dwordx4 v[154:155], v[0:3], off offset:1152 nt
	s_nop 1
	v_pk_mul_f32 v[0:1], v[54:55], v[58:59] op_sel_hi:[1,0]
	v_pk_mul_f32 v[2:3], v[84:85], v[58:59] op_sel_hi:[1,0]
	v_pk_mul_f32 v[8:9], v[52:53], v[0:1]
	v_pk_mul_f32 v[10:11], v[82:83], v[2:3]
	global_store_dwordx4 v[154:155], v[0:3], off offset:448 nt
	global_store_dwordx4 v[154:155], v[8:11], off offset:704 nt
	s_nop 0
	v_pk_fma_f32 v[2:3], v[22:23], v[2:3], v[6:7] op_sel_hi:[0,1,1] neg_lo:[1,0,0] neg_hi:[1,0,0]
	v_pk_fma_f32 v[0:1], v[22:23], v[0:1], v[4:5] op_sel_hi:[0,1,1] neg_lo:[1,0,0] neg_hi:[1,0,0]
	global_store_dwordx4 v[154:155], v[0:3], off offset:1216 nt
	s_and_saveexec_b64 s[0:1], vcc
	s_cbranch_execz .LBB0_477
	v_readlane_b32 s20, v214, 10
	v_lshlrev_b64 v[0:1], 7, v[134:135]
	v_readlane_b32 s21, v214, 11
	s_waitcnt lgkmcnt(1)
	v_add_f32_e32 v64, v24, v26
	s_waitcnt lgkmcnt(0)
	v_add_f32_e32 v62, v23, v25
	v_lshl_add_u64 v[0:1], s[20:21], 0, v[0:1]
	v_lshl_add_u64 v[0:1], v[148:149], 4, v[0:1]
	v_mov_b32_e32 v63, v22
	global_store_dwordx4 v[0:1], v[62:65], off
	s_or_b64 exec, exec, s[0:1]
	s_and_saveexec_b64 s[0:1], s[40:41]
	s_xor_b64 s[0:1], exec, s[0:1]
	s_cbranch_execnz .LBB0_478

	.amdhsa_kernel _Z4mega6Params
		.amdhsa_group_segment_fixed_size 0
		.amdhsa_private_segment_fixed_size 0
		.amdhsa_kernarg_size 488
		.amdhsa_user_sgpr_count 2
		.amdhsa_user_sgpr_dispatch_ptr 0
		.amdhsa_user_sgpr_queue_ptr 0
		.amdhsa_user_sgpr_kernarg_segment_ptr 1
		.amdhsa_user_sgpr_dispatch_id 0
		.amdhsa_user_sgpr_kernarg_preload_length 0
		.amdhsa_user_sgpr_kernarg_preload_offset 0
		.amdhsa_user_sgpr_private_segment_size 0
		.amdhsa_uses_dynamic_stack 0
		.amdhsa_enable_private_segment 0
		.amdhsa_system_sgpr_workgroup_id_x 1
		.amdhsa_system_sgpr_workgroup_id_y 0
		.amdhsa_system_sgpr_workgroup_id_z 0
		.amdhsa_system_sgpr_workgroup_info 0
		.amdhsa_system_vgpr_workitem_id 2
		.amdhsa_next_free_vgpr 256
		.amdhsa_next_free_sgpr 100
		.amdhsa_accum_offset 220
		.amdhsa_reserve_vcc 1
		.amdhsa_float_round_mode_32 0
		.amdhsa_float_round_mode_16_64 0
		.amdhsa_float_denorm_mode_32 3
		.amdhsa_float_denorm_mode_16_64 3
		.amdhsa_dx10_clamp 1
		.amdhsa_ieee_mode 1
		.amdhsa_fp16_overflow 0
		.amdhsa_tg_split 0
		.amdhsa_exception_fp_ieee_invalid_op 0
		.amdhsa_exception_fp_denorm_src 0
		.amdhsa_exception_fp_ieee_div_zero 0
		.amdhsa_exception_fp_ieee_overflow 0
		.amdhsa_exception_fp_ieee_underflow 0
		.amdhsa_exception_fp_ieee_inexact 0
		.amdhsa_exception_int_div_zero 0
	.end_amdhsa_kernel

amdhsa.kernels:
  - .agpr_count:     36
    .args:
      - .offset:         0
        .size:           232
        .value_kind:     by_value
      - .offset:         232
        .size:           4
        .value_kind:     hidden_block_count_x
      - .offset:         236
        .size:           4
        .value_kind:     hidden_block_count_y
      - .offset:         240
        .size:           4
        .value_kind:     hidden_block_count_z
      - .offset:         244
        .size:           2
        .value_kind:     hidden_group_size_x
      - .offset:         246
        .size:           2
        .value_kind:     hidden_group_size_y
      - .offset:         248
        .size:           2
        .value_kind:     hidden_group_size_z
      - .offset:         250
        .size:           2
        .value_kind:     hidden_remainder_x
      - .offset:         252
        .size:           2
        .value_kind:     hidden_remainder_y
      - .offset:         254
        .size:           2
        .value_kind:     hidden_remainder_z
      - .offset:         272
        .size:           8
        .value_kind:     hidden_global_offset_x
      - .offset:         280
        .size:           8
        .value_kind:     hidden_global_offset_y
      - .offset:         288
        .size:           8
        .value_kind:     hidden_global_offset_z
      - .offset:         296
        .size:           2
        .value_kind:     hidden_grid_dims
      - .offset:         320
        .size:           8
        .value_kind:     hidden_multigrid_sync_arg
      - .offset:         352
        .size:           4
        .value_kind:     hidden_dynamic_lds_size
    .group_segment_fixed_size: 0
    .kernarg_segment_align: 8
    .kernarg_segment_size: 488
    .language:       OpenCL C
    .language_version:
      - 2
      - 0
    .max_flat_workgroup_size: 512
    .name:           _Z4mega6Params
    .private_segment_fixed_size: 0
    .sgpr_count:     106
    .sgpr_spill_count: 308
    .symbol:         _Z4mega6Params.kd
    .uniform_work_group_size: 1
    .uses_dynamic_stack: false
    .vgpr_count:     217
    .vgpr_spill_count: 0
    .wavefront_size: 64
